# GLA scan overlapped with dilated attention: attention moved behind the summary->scan barrier, waves 0-3 scan first, waves 4-7 attention first
# speedup vs baseline: 1.0089x; 1.0060x over previous
; __device__ void phase_gla_scan(const P& p) {
;   u16* kv = (u16*)((char*)p.out + OUT_KV);
;   const float* dec = (const float*)(p.ws + OFF_DEC);
;   int tid = opaque_tid(p);
;   for (int it = blockIdx.x; it < 768; it += gridDim.x) {
;     int chunk0, nc, q;
;     if (it < 256) { q = it; int seq = q >> 6; chunk0 = 512 + seq * 128; nc = 128; q &= 63; }
;     else { q = it - 256; int seq = q >> 6; chunk0 = seq * 64; nc = 64; q &= 63; }
;     int h = q >> 4, dir = (q >> 3) & 1, sl = q & 7;
;     int e0 = sl * 1024 + tid * 2;
;     int dk = e0 & 63;
.Lmy_scan:
	s_cmpk_gt_i32 s2, 0x2ff
	v_mbcnt_lo_u32_b32 v0, -1, 0
	v_mbcnt_hi_u32_b32 v0, -1, v0
	s_cbranch_scc1 .Lmy_scan_done
	v_readlane_b32 s0, v255, 0
	s_lshl_b32 s0, s0, 1
	s_and_b32 s0, s0, 0xffffff80
	v_lshl_add_u32 v8, v0, 1, s0
	v_and_b32_e32 v0, 3, v0
	v_lshlrev_b32_e32 v0, 3, v0
	s_lshr_b32 s0, s33, 1
	v_add_u32_e32 v0, s0, v0
	v_mov_b32_e32 v1, 0
	v_lshl_add_u64 v[0:1], s[34:35], 0, v[0:1]
	s_mov_b64 s[0:1], 0x1f400000
	v_lshl_add_u64 v[0:1], v[0:1], 0, s[0:1]
	s_mov_b32 s3, s2
